# SB unit: static priority raise for waves 4-7 (one wave of each SIMD pair)
# baseline (speedup 1.0000x reference)
.LBB0_332:
	s_or_b64 exec, exec, s[2:3]
	s_waitcnt lgkmcnt(0)
	s_barrier
	ds_read_b32 v0, v229
	s_movk_i32 s2, 0x3ff
	s_waitcnt lgkmcnt(0)
	v_cmp_lt_i32_e32 vcc, s2, v0
	v_readfirstlane_b32 s97, v0
	s_mov_b64 s[2:3], -1
	s_cbranch_vccnz .LBB0_301
	s_cmpk_gt_i32 s97, 0x1ff
	s_cbranch_scc0 .LBB0_385
	s_cmp_lt_u32 s63, 4
	s_cbranch_scc1 .Lsb_noprio
	s_setprio 1
.Lsb_noprio:
	s_add_i32 s2, s97, 0xfffffe00
	s_lshr_b32 s99, s2, 6
	s_sub_i32 s6, 7, s99
	s_bfe_u32 s3, s97, 0x30003
	s_lshl_b32 s66, s6, 8
	v_readlane_b32 s2, v254, 53
	s_and_b32 s4, s97, 7
	s_add_i32 s66, s66, s2
	s_lshl_b32 s2, s3, 21
	v_mov_b32_e32 v82, v231
	v_writelane_b32 v255, s3, 49
	s_add_u32 s2, s78, s2
	s_addc_u32 s3, s79, 0
	v_and_b32_e32 v3, 31, v82
	v_writelane_b32 v255, s4, 50
	s_lshl_b32 s4, s4, 18
	v_ashrrev_i32_e32 v2, 5, v82
	v_or_b32_e32 v0, s66, v3
	s_add_u32 s2, s2, s4
	s_addc_u32 s3, s3, 0
	v_lshlrev_b64 v[4:5], 7, v[0:1]
	v_lshlrev_b32_e32 v114, 3, v2
	v_lshl_add_u64 v[4:5], s[2:3], 0, v[4:5]
	v_ashrrev_i32_e32 v115, 31, v114
	v_lshl_add_u64 v[4:5], v[114:115], 1, v[4:5]
	global_load_dwordx4 v[98:101], v[4:5], off
	global_load_dwordx4 v[102:105], v[4:5], off offset:32
	global_load_dwordx4 v[106:109], v[4:5], off offset:64
	global_load_dwordx4 v[110:113], v[4:5], off offset:96
	v_cmp_gt_i32_e32 vcc, 2, v82
	s_and_saveexec_b64 s[4:5], vcc
	v_lshl_add_u32 v4, v82, 5, s94
	ds_write_b32 v4, v1
	s_or_b64 exec, exec, s[4:5]
	v_ashrrev_i32_e32 v4, 3, v82
	v_readlane_b32 s4, v254, 54
	v_mov_b32_e32 v7, v1
	v_mov_b32_e32 v9, v1
	v_add_u32_e32 v4, s4, v4
	v_lshrrev_b32_e32 v5, 1, v4
	v_xor_b32_e32 v6, v5, v82
	v_lshlrev_b32_e32 v4, 6, v4
	v_ashrrev_i32_e32 v5, 31, v4
	v_lshlrev_b32_e32 v6, 4, v6
	v_lshl_add_u64 v[4:5], v[4:5], 1, s[2:3]
	v_and_b32_e32 v6, 0x70, v6
	v_lshl_add_u64 v[4:5], v[4:5], 0, v[6:7]
	s_mov_b64 s[4:5], 0x1000000
	v_lshl_add_u64 v[116:117], v[4:5], 0, s[4:5]
	v_add_u32_e32 v5, s30, v114
	v_lshrrev_b32_e32 v4, 2, v82
	v_and_or_b32 v5, v4, 7, v5
	v_lshlrev_b32_e32 v6, 3, v82
	v_and_b32_e32 v126, 24, v6
	v_lshlrev_b32_e32 v6, 6, v5
	v_ashrrev_i32_e32 v7, 31, v6
	v_lshl_add_u64 v[6:7], v[6:7], 1, s[2:3]
	v_lshlrev_b32_e32 v8, 1, v126
	v_lshl_add_u64 v[6:7], v[6:7], 0, v[8:9]
	s_mov_b64 s[4:5], 0x2000000
	v_lshl_add_u64 v[118:119], v[6:7], 0, s[4:5]
	s_lshl_b32 s4, s6, 2
	s_add_i32 s80, s0, s4
	s_add_i32 s4, s80, 1
	s_mov_b32 s5, s81
	s_lshl_b64 s[6:7], s[4:5], 13
	v_lshl_add_u64 v[6:7], v[116:117], 0, s[6:7]
	s_mov_b64 s[10:11], 0x1000
	v_readlane_b32 s8, v255, 8
	s_mov_b32 s5, m0
	s_mov_b32 m0, s8
	s_nop 0
	global_load_lds_dwordx4 v[6:7], off
	s_mov_b32 m0, s5
	v_lshl_add_u64 v[6:7], v[6:7], 0, s[10:11]
	v_readlane_b32 s8, v254, 56
	s_mov_b32 s5, m0
	s_mov_b32 m0, s8
	s_nop 0
	global_load_lds_dwordx4 v[6:7], off
	s_mov_b32 m0, s5
	v_lshl_add_u64 v[6:7], v[118:119], 0, s[6:7]
	v_readlane_b32 s6, v254, 57
	s_mov_b32 s5, m0
	s_mov_b32 m0, s6
	s_nop 0
	global_load_lds_dwordx4 v[6:7], off
	s_mov_b32 m0, s5
	v_readlane_b32 s6, v254, 58
	v_lshl_add_u64 v[6:7], v[6:7], 0, 64
	s_mov_b32 s5, m0
	s_mov_b32 m0, s6
	s_nop 0
	global_load_lds_dwordx4 v[6:7], off
	s_mov_b32 m0, s5
	s_lshl_b64 s[6:7], s[80:81], 13
	v_lshl_add_u64 v[6:7], v[116:117], 0, s[6:7]
	v_readlane_b32 s8, v254, 59
	s_mov_b32 s5, m0
	s_mov_b32 m0, s8
	s_nop 0
	global_load_lds_dwordx4 v[6:7], off
	s_mov_b32 m0, s5
	v_lshl_add_u64 v[6:7], v[6:7], 0, s[10:11]
	v_readlane_b32 s8, v254, 60
	s_mov_b32 s5, m0
	s_mov_b32 m0, s8
	s_nop 0
	global_load_lds_dwordx4 v[6:7], off
	s_mov_b32 m0, s5
	v_lshl_add_u64 v[6:7], v[118:119], 0, s[6:7]
	v_readlane_b32 s6, v254, 61
	s_mov_b32 s5, m0
	s_mov_b32 m0, s6
	s_nop 0
	global_load_lds_dwordx4 v[6:7], off
	s_mov_b32 m0, s5
	v_lshl_add_u64 v[6:7], v[6:7], 0, 64
	v_readlane_b32 s8, v254, 62
	s_mov_b32 s5, m0
	s_mov_b32 m0, s8
	s_nop 0
	global_load_lds_dwordx4 v[6:7], off
	s_mov_b32 m0, s5
	s_cmp_lg_u32 s4, 1
	s_mov_b64 s[78:79], 0x1000
	s_cselect_b64 s[6:7], -1, 0
	s_cmp_eq_u32 s4, 1
	s_cbranch_scc1 .LBB0_338
	s_add_i32 s80, s4, -2
	s_lshl_b64 s[8:9], s[80:81], 13
	v_lshl_add_u64 v[6:7], v[116:117], 0, s[8:9]
	v_readlane_b32 s10, v254, 63
	s_mov_b32 s5, m0
	s_mov_b32 m0, s10
	s_nop 0
	global_load_lds_dwordx4 v[6:7], off
	s_mov_b32 m0, s5
	v_lshl_add_u64 v[6:7], v[6:7], 0, s[78:79]
	v_readlane_b32 s10, v255, 0
	s_mov_b32 s5, m0
	s_mov_b32 m0, s10
	s_nop 0
	global_load_lds_dwordx4 v[6:7], off
	s_mov_b32 m0, s5
	v_lshl_add_u64 v[6:7], v[118:119], 0, s[8:9]
	v_readlane_b32 s8, v255, 1
	s_mov_b32 s5, m0
	s_mov_b32 m0, s8
	s_nop 0
	global_load_lds_dwordx4 v[6:7], off
	s_mov_b32 m0, s5
	v_lshl_add_u64 v[6:7], v[6:7], 0, 64
	v_readlane_b32 s8, v255, 2
	s_mov_b32 s5, m0
	s_mov_b32 m0, s8
	s_nop 0
	global_load_lds_dwordx4 v[6:7], off
	s_mov_b32 m0, s5

.LBB0_384:
	s_or_b64 exec, exec, s[4:5]
	v_lshl_add_u64 v[34:35], v[120:121], 1, s[2:3]
	s_waitcnt lgkmcnt(9)
	v_lshlrev_b64 v[46:47], 1, v[114:115]
	v_lshl_add_u64 v[34:35], v[34:35], 0, v[46:47]
	s_mov_b64 s[2:3], 0x3000000
	v_lshl_add_u64 v[36:37], v[34:35], 0, s[2:3]
	v_add_co_u32_e32 v34, vcc, 0x3000000, v34
	v_readlane_b32 s2, v255, 49
	s_nop 0
	v_addc_co_u32_e32 v35, vcc, 0, v35, vcc
	s_waitcnt lgkmcnt(7)
	s_nop 0
	v_lshl_add_u32 v0, s2, 11, v0
	s_waitcnt lgkmcnt(6)
	v_lshlrev_b64 v[52:53], 11, v[0:1]
	v_readlane_b32 s2, v255, 50
	v_lshl_add_u64 v[52:53], s[56:57], 0, v[52:53]
	s_lshl_b32 s80, s2, 7
	v_lshl_add_u64 v[52:53], v[52:53], 0, s[80:81]
	v_lshl_add_u64 v[46:47], v[52:53], 0, v[46:47]
	s_waitcnt lgkmcnt(0)
	s_barrier
	v_mov_b32_e32 v48, v192
	v_mov_b32_e32 v49, v193
	v_mov_b32_e32 v42, v218
	v_mov_b32_e32 v43, v219
	v_mov_b32_e32 v44, v220
	v_mov_b32_e32 v45, v221
	v_mov_b32_e32 v38, v222
	v_mov_b32_e32 v39, v223
	v_mov_b32_e32 v40, v224
	v_mov_b32_e32 v41, v225
	v_mov_b32_e32 v34, v240
	v_mov_b32_e32 v35, v241
	v_mov_b32_e32 v36, v242
	v_mov_b32_e32 v37, v243
	s_mov_b64 s[2:3], 0
	v_mov_b32_e32 v0, v194
	s_nop 1
	v_permlane32_swap_b32_e32 v48, v0
	v_lshlrev_b32_e32 v50, 16, v48
	s_waitcnt lgkmcnt(3)
	v_mov_b32_e32 v54, v195
	v_and_b32_e32 v51, 0xffff0000, v48
	v_mul_f32_e32 v48, 0xbfb8aa3b, v50
	v_exp_f32_e32 v48, v48
	v_permlane32_swap_b32_e32 v49, v54
	v_add_f32_e32 v48, 1.0, v48
	v_rcp_f32_e32 v52, v48
	v_mul_f32_e32 v48, 0xbfb8aa3b, v51
	v_exp_f32_e32 v48, v48
	s_nop 0
	v_add_f32_e32 v48, 1.0, v48
	v_rcp_f32_e32 v53, v48
	v_lshlrev_b32_e32 v48, 16, v49
	v_and_b32_e32 v49, 0xffff0000, v49
	v_mul_f32 v50, v52, v50
	v_mul_f32 v51, v53, v51
	s_nop 0
	v_mul_f32 v18, v18, v50
	v_mul_f32 v19, v19, v51
	s_nop 0
	v_cvt_pk_bf16_f32 v18, v18, v19
	v_mul_f32_e32 v19, 0xbfb8aa3b, v48
	v_exp_f32_e32 v19, v19
	s_nop 0
	v_add_f32_e32 v19, 1.0, v19
	v_rcp_f32_e32 v50, v19
	v_mul_f32_e32 v19, 0xbfb8aa3b, v49
	v_exp_f32_e32 v19, v19
	s_nop 0
	v_add_f32_e32 v19, 1.0, v19
	v_rcp_f32_e32 v51, v19
	s_nop 0
	v_mul_f32 v48, v50, v48
	v_mul_f32 v49, v51, v49
	s_nop 0
	v_mul_f32 v20, v20, v48
	v_mul_f32 v21, v21, v49
	s_nop 0
	v_cvt_pk_bf16_f32 v19, v20, v21
	v_lshlrev_b32_e32 v20, 16, v0
	v_and_b32_e32 v21, 0xffff0000, v0
	v_mul_f32_e32 v0, 0xbfb8aa3b, v20
	v_exp_f32_e32 v0, v0
	s_nop 0
	v_add_f32_e32 v0, 1.0, v0
	v_rcp_f32_e32 v48, v0
	v_mul_f32_e32 v0, 0xbfb8aa3b, v21
	v_exp_f32_e32 v0, v0
	s_nop 0
	v_add_f32_e32 v0, 1.0, v0
	v_rcp_f32_e32 v49, v0
	s_nop 0
	v_mul_f32 v20, v48, v20
	v_mul_f32 v21, v49, v21
	s_nop 0
	v_mul_f32 v20, v22, v20
	v_mul_f32 v21, v23, v21
	v_lshlrev_b32_e32 v22, 16, v54
	v_mul_f32_e32 v0, 0xbfb8aa3b, v22
	v_exp_f32_e32 v0, v0
	v_and_b32_e32 v23, 0xffff0000, v54
	v_cvt_pk_bf16_f32 v20, v20, v21
	s_nop 1
	v_permlane32_swap_b32_e32 v18, v20
	v_add_f32_e32 v0, 1.0, v0
	v_rcp_f32_e32 v48, v0
	v_mul_f32_e32 v0, 0xbfb8aa3b, v23
	v_exp_f32_e32 v0, v0
	s_nop 0
	v_add_f32_e32 v0, 1.0, v0
	v_rcp_f32_e32 v49, v0
	v_mov_b32_e32 v0, v44
	s_nop 1
	v_permlane32_swap_b32_e32 v42, v0
	v_mul_f32 v22, v48, v22
	v_mul_f32 v23, v49, v23
	s_nop 0
	v_mul_f32 v22, v24, v22
	v_mul_f32 v23, v25, v23
	s_nop 0
	v_cvt_pk_bf16_f32 v21, v22, v23
	s_nop 1
	v_permlane32_swap_b32_e32 v19, v21
	global_store_dwordx4 v[46:47], v[18:21], off
	v_mov_b32_e32 v22, v45
	s_nop 1
	v_permlane32_swap_b32_e32 v43, v22
	v_lshlrev_b32_e32 v18, 16, v42
	v_and_b32_e32 v19, 0xffff0000, v42
	v_mul_f32_e32 v20, 0xbfb8aa3b, v18
	v_mul_f32_e32 v21, 0xbfb8aa3b, v19
	v_exp_f32_e32 v20, v20
	v_exp_f32_e32 v21, v21
	v_add_f32_e32 v20, 1.0, v20
	v_add_f32_e32 v21, 1.0, v21
	v_rcp_f32_e32 v20, v20
	v_rcp_f32_e32 v21, v21
	s_nop 0
	v_mul_f32 v18, v20, v18
	v_mul_f32 v19, v21, v19
	s_nop 0
	v_mul_f32 v2, v2, v18
	v_mul_f32 v3, v3, v19
	v_lshlrev_b32_e32 v18, 16, v43
	v_cvt_pk_bf16_f32 v2, v2, v3
	v_mul_f32_e32 v3, 0xbfb8aa3b, v18
	v_exp_f32_e32 v3, v3
	v_and_b32_e32 v19, 0xffff0000, v43
	v_add_f32_e32 v3, 1.0, v3
	v_rcp_f32_e32 v20, v3
	v_mul_f32_e32 v3, 0xbfb8aa3b, v19
	v_exp_f32_e32 v3, v3
	s_nop 0
	v_add_f32_e32 v3, 1.0, v3
	v_rcp_f32_e32 v21, v3
	s_nop 0
	v_mul_f32 v18, v20, v18
	v_mul_f32 v19, v21, v19
	s_nop 0
	v_mul_f32 v4, v4, v18
	v_mul_f32 v5, v5, v19
	s_nop 0
	v_cvt_pk_bf16_f32 v3, v4, v5
	v_lshlrev_b32_e32 v4, 16, v0
	v_and_b32_e32 v5, 0xffff0000, v0
	v_mul_f32_e32 v0, 0xbfb8aa3b, v4
	v_exp_f32_e32 v0, v0
	s_nop 0
	v_add_f32_e32 v0, 1.0, v0
	v_rcp_f32_e32 v18, v0
	v_mul_f32_e32 v0, 0xbfb8aa3b, v5
	v_exp_f32_e32 v0, v0
	s_nop 0
	v_add_f32_e32 v0, 1.0, v0
	v_rcp_f32_e32 v19, v0
	s_nop 0
	v_mul_f32 v4, v18, v4
	v_mul_f32 v5, v19, v5
	s_nop 0
	v_mul_f32 v4, v6, v4
	v_mul_f32 v5, v7, v5
	v_lshlrev_b32_e32 v6, 16, v22
	v_mul_f32_e32 v0, 0xbfb8aa3b, v6
	v_exp_f32_e32 v0, v0
	v_and_b32_e32 v7, 0xffff0000, v22
	v_cvt_pk_bf16_f32 v4, v4, v5
	s_nop 1
	v_permlane32_swap_b32_e32 v2, v4
	v_add_f32_e32 v0, 1.0, v0
	v_rcp_f32_e32 v18, v0
	v_mul_f32_e32 v0, 0xbfb8aa3b, v7
	v_exp_f32_e32 v0, v0
	s_nop 0
	v_add_f32_e32 v0, 1.0, v0
	v_rcp_f32_e32 v19, v0
	v_mov_b32_e32 v0, v40
	s_nop 1
	v_permlane32_swap_b32_e32 v38, v0
	v_mul_f32 v6, v18, v6
	v_mul_f32 v7, v19, v7
	s_nop 0
	v_mul_f32 v6, v8, v6
	v_mul_f32 v7, v9, v7
	v_mov_b32_e32 v8, v41
	v_cvt_pk_bf16_f32 v5, v6, v7
	s_nop 1
	v_permlane32_swap_b32_e32 v3, v5
	global_store_dwordx4 v[46:47], v[2:5], off offset:64
	v_permlane32_swap_b32_e32 v39, v8
	s_nop 0
	v_lshlrev_b32_e32 v2, 16, v38
	v_and_b32_e32 v3, 0xffff0000, v38
	v_mul_f32_e32 v4, 0xbfb8aa3b, v2
	v_mul_f32_e32 v5, 0xbfb8aa3b, v3
	v_exp_f32_e32 v4, v4
	v_exp_f32_e32 v5, v5
	v_add_f32_e32 v4, 1.0, v4
	v_add_f32_e32 v5, 1.0, v5
	v_rcp_f32_e32 v4, v4
	v_rcp_f32_e32 v5, v5
	s_nop 0
	v_mul_f32 v2, v4, v2
	v_mul_f32 v3, v5, v3
	s_nop 0
	v_mul_f32 v2, v26, v2
	v_mul_f32 v3, v27, v3
	v_lshlrev_b32_e32 v4, 16, v39
	v_cvt_pk_bf16_f32 v2, v2, v3
	v_mul_f32_e32 v3, 0xbfb8aa3b, v4
	v_exp_f32_e32 v3, v3
	v_and_b32_e32 v5, 0xffff0000, v39
	v_add_f32_e32 v3, 1.0, v3
	v_rcp_f32_e32 v6, v3
	v_mul_f32_e32 v3, 0xbfb8aa3b, v5
	v_exp_f32_e32 v3, v3
	s_nop 0
	v_add_f32_e32 v3, 1.0, v3
	v_rcp_f32_e32 v7, v3
	s_nop 0
	v_mul_f32 v4, v6, v4
	v_mul_f32 v5, v7, v5
	s_nop 0
	v_mul_f32 v4, v28, v4
	v_mul_f32 v5, v29, v5
	s_nop 0
	v_cvt_pk_bf16_f32 v3, v4, v5
	v_lshlrev_b32_e32 v4, 16, v0
	v_and_b32_e32 v5, 0xffff0000, v0
	v_mul_f32_e32 v0, 0xbfb8aa3b, v4
	v_exp_f32_e32 v0, v0
	s_nop 0
	v_add_f32_e32 v0, 1.0, v0
	v_rcp_f32_e32 v6, v0
	v_mul_f32_e32 v0, 0xbfb8aa3b, v5
	v_exp_f32_e32 v0, v0
	s_nop 0
	v_add_f32_e32 v0, 1.0, v0
	v_rcp_f32_e32 v7, v0
	s_nop 0
	v_mul_f32 v4, v6, v4
	v_mul_f32 v5, v7, v5
	v_lshlrev_b32_e32 v6, 16, v8
	v_mul_f32_e32 v0, 0xbfb8aa3b, v6
	v_exp_f32_e32 v0, v0
	v_and_b32_e32 v7, 0xffff0000, v8
	v_mul_f32 v4, v30, v4
	v_mul_f32 v5, v31, v5
	v_add_f32_e32 v0, 1.0, v0
	v_rcp_f32_e32 v8, v0
	v_mul_f32_e32 v0, 0xbfb8aa3b, v7
	v_exp_f32_e32 v0, v0
	v_cvt_pk_bf16_f32 v4, v4, v5
	s_nop 1
	v_permlane32_swap_b32_e32 v2, v4
	v_add_f32_e32 v0, 1.0, v0
	v_rcp_f32_e32 v9, v0
	v_mov_b32_e32 v0, v36
	s_nop 1
	v_permlane32_swap_b32_e32 v34, v0
	v_mul_f32 v6, v8, v6
	v_mul_f32 v7, v9, v7
	v_mov_b32_e32 v8, v37
	v_mul_f32 v6, v32, v6
	v_mul_f32 v7, v33, v7
	s_nop 0
	v_permlane32_swap_b32_e32 v35, v8
	v_cvt_pk_bf16_f32 v5, v6, v7
	s_nop 1
	v_permlane32_swap_b32_e32 v3, v5
	global_store_dwordx4 v[46:47], v[2:5], off offset:32
	s_nop 1
	v_lshlrev_b32_e32 v2, 16, v34
	v_and_b32_e32 v3, 0xffff0000, v34
	v_mul_f32_e32 v4, 0xbfb8aa3b, v2
	v_mul_f32_e32 v5, 0xbfb8aa3b, v3
	v_exp_f32_e32 v4, v4
	v_exp_f32_e32 v5, v5
	v_add_f32_e32 v4, 1.0, v4
	v_add_f32_e32 v5, 1.0, v5
	v_rcp_f32_e32 v4, v4
	v_rcp_f32_e32 v5, v5
	s_nop 0
	v_mul_f32 v2, v4, v2
	v_mul_f32 v3, v5, v3
	s_nop 0
	v_mul_f32 v2, v10, v2
	v_mul_f32 v3, v11, v3
	v_lshlrev_b32_e32 v4, 16, v35
	v_cvt_pk_bf16_f32 v2, v2, v3
	v_mul_f32_e32 v3, 0xbfb8aa3b, v4
	v_exp_f32_e32 v3, v3
	v_and_b32_e32 v5, 0xffff0000, v35
	v_add_f32_e32 v3, 1.0, v3
	v_rcp_f32_e32 v6, v3
	v_mul_f32_e32 v3, 0xbfb8aa3b, v5
	v_exp_f32_e32 v3, v3
	s_nop 0
	v_add_f32_e32 v3, 1.0, v3
	v_rcp_f32_e32 v7, v3
	s_nop 0
	v_mul_f32 v4, v6, v4
	v_mul_f32 v5, v7, v5
	s_nop 0
	v_mul_f32 v4, v12, v4
	v_mul_f32 v5, v13, v5
	s_nop 0
	v_cvt_pk_bf16_f32 v3, v4, v5
	v_lshlrev_b32_e32 v4, 16, v0
	v_and_b32_e32 v5, 0xffff0000, v0
	v_mul_f32_e32 v0, 0xbfb8aa3b, v4
	v_exp_f32_e32 v0, v0
	s_nop 0
	v_add_f32_e32 v0, 1.0, v0
	v_rcp_f32_e32 v6, v0
	v_mul_f32_e32 v0, 0xbfb8aa3b, v5
	v_exp_f32_e32 v0, v0
	s_nop 0
	v_add_f32_e32 v0, 1.0, v0
	v_rcp_f32_e32 v7, v0
	s_nop 0
	v_mul_f32 v4, v6, v4
	v_mul_f32 v5, v7, v5
	v_lshlrev_b32_e32 v6, 16, v8
	v_mul_f32_e32 v0, 0xbfb8aa3b, v6
	v_exp_f32_e32 v0, v0
	v_and_b32_e32 v7, 0xffff0000, v8
	v_mul_f32 v4, v14, v4
	v_mul_f32 v5, v15, v5
	v_add_f32_e32 v0, 1.0, v0
	v_rcp_f32_e32 v8, v0
	v_mul_f32_e32 v0, 0xbfb8aa3b, v7
	v_exp_f32_e32 v0, v0
	v_cvt_pk_bf16_f32 v4, v4, v5
	s_nop 1
	v_permlane32_swap_b32_e32 v2, v4
	v_add_f32_e32 v0, 1.0, v0
	v_rcp_f32_e32 v9, v0
	s_nop 0
	v_mul_f32 v6, v8, v6
	v_mul_f32 v7, v9, v7
	s_nop 0
	v_mul_f32 v6, v16, v6
	v_mul_f32 v7, v17, v7
	s_nop 0
	v_cvt_pk_bf16_f32 v5, v6, v7
	s_nop 1
	v_permlane32_swap_b32_e32 v3, v5
	global_store_dwordx4 v[46:47], v[2:5], off offset:96
	s_waitcnt vmcnt(4)
	v_min_u32_e32 v253, 0xffff, v253
	v_or_b32_e32 v95, v95, v253
	s_setprio 0
